# lru_carry: loop-invariant base and stride setup hoisted out of the trip loop
# speedup vs baseline: 1.0030x; 1.0009x over previous
; __device__ __forceinline__ int otid() { int t = __builtin_amdgcn_workitem_id_x(); asm volatile("" : "+v"(t)); return t; }
; __device__ __forceinline__ int obid() { int b = __builtin_amdgcn_workgroup_id_x(); asm volatile("" : "+s"(b)); return b; }
; __device__ __forceinline__ void lru_carry(const float* __restrict__ LSUM, float* __restrict__ LCAR) {
;     for (int id = obid() * 512 + otid(); id < 2048; id += gridDim.x * 512) {
;         const int b = id >> 10, g = (id >> 9) & 1, ch = id & 511; float c = 0.f;
;         for (int st = 0; st < 256; ++st) { const int seg = g ? 255 - st : st; const size_t ix = ((size_t)(b * 256 + seg) * 2 + g) * 512 + ch;
;             LCAR[ix] = c; c = LSUM[2 * ix] * c + LSUM[2 * ix + 1]; }
;     }
; }
.LBB0_502:
	v_and_b32_e32 v2, 0x200, v1
	v_cmp_eq_u32_e32 vcc, 0, v2
	v_ashrrev_i32_e32 v2, 2, v1
	s_mov_b32 s4, 0
	s_waitcnt lgkmcnt(0)
	v_and_b32_e32 v3, 0xffffff00, v2
	v_and_b32_e32 v2, 0x3ff, v1
	s_waitcnt vmcnt(0)
	v_mov_b32_e32 v7, 0
	s_movk_i32 s5, 0xf8
	v_readlane_b32 s2, v251, 10
	v_readlane_b32 s3, v251, 11
	v_mov_b32_e32 v74, 0xfffff000
	v_mov_b32_e32 v5, 0x1000
	v_cndmask_b32_e32 v74, v74, v5, vcc
	v_ashrrev_i32_e32 v75, 31, v74
	v_lshlrev_b32_e32 v76, 1, v74
	v_mov_b32_e32 v77, v75
.LBB0_503:
	s_add_i32 s7, s5, 7
	v_mov_b32_e32 v4, s7
	v_mov_b32_e32 v5, s4
	v_cndmask_b32_e32 v4, v4, v5, vcc
	v_or_b32_e32 v4, v4, v3
	v_ashrrev_i32_e32 v5, 31, v4
	v_lshlrev_b64 v[4:5], 10, v[4:5]
	v_or_b32_e32 v4, v4, v2
	v_lshl_add_u64 v[42:43], v[4:5], 2, s[2:3]
	v_lshl_add_u64 v[4:5], v[4:5], 3, s[30:31]
	global_load_dwordx2 v[10:11], v[4:5], off
	v_lshl_add_u64 v[4:5], v[4:5], 0, v[76:77]
	v_lshl_add_u64 v[44:45], v[42:43], 0, v[74:75]
	global_load_dwordx2 v[12:13], v[4:5], off
	v_lshl_add_u64 v[4:5], v[4:5], 0, v[76:77]
	v_lshl_add_u64 v[46:47], v[44:45], 0, v[74:75]
	global_load_dwordx2 v[14:15], v[4:5], off
	v_lshl_add_u64 v[4:5], v[4:5], 0, v[76:77]
	v_lshl_add_u64 v[48:49], v[46:47], 0, v[74:75]
	global_load_dwordx2 v[16:17], v[4:5], off
	v_lshl_add_u64 v[4:5], v[4:5], 0, v[76:77]
	v_lshl_add_u64 v[50:51], v[48:49], 0, v[74:75]
	global_load_dwordx2 v[18:19], v[4:5], off
	v_lshl_add_u64 v[4:5], v[4:5], 0, v[76:77]
	v_lshl_add_u64 v[52:53], v[50:51], 0, v[74:75]
	global_load_dwordx2 v[20:21], v[4:5], off
	v_lshl_add_u64 v[4:5], v[4:5], 0, v[76:77]
	v_lshl_add_u64 v[54:55], v[52:53], 0, v[74:75]
	global_load_dwordx2 v[22:23], v[4:5], off
	v_lshl_add_u64 v[4:5], v[4:5], 0, v[76:77]
	v_lshl_add_u64 v[56:57], v[54:55], 0, v[74:75]
	global_load_dwordx2 v[24:25], v[4:5], off
	v_lshl_add_u64 v[4:5], v[4:5], 0, v[76:77]
	v_lshl_add_u64 v[58:59], v[56:57], 0, v[74:75]
	global_load_dwordx2 v[26:27], v[4:5], off
	v_lshl_add_u64 v[4:5], v[4:5], 0, v[76:77]
	v_lshl_add_u64 v[60:61], v[58:59], 0, v[74:75]
	global_load_dwordx2 v[28:29], v[4:5], off
	v_lshl_add_u64 v[4:5], v[4:5], 0, v[76:77]
	v_lshl_add_u64 v[62:63], v[60:61], 0, v[74:75]
	global_load_dwordx2 v[30:31], v[4:5], off
	v_lshl_add_u64 v[4:5], v[4:5], 0, v[76:77]
	v_lshl_add_u64 v[64:65], v[62:63], 0, v[74:75]
	global_load_dwordx2 v[32:33], v[4:5], off
	v_lshl_add_u64 v[4:5], v[4:5], 0, v[76:77]
	v_lshl_add_u64 v[66:67], v[64:65], 0, v[74:75]
	global_load_dwordx2 v[34:35], v[4:5], off
	v_lshl_add_u64 v[4:5], v[4:5], 0, v[76:77]
	v_lshl_add_u64 v[68:69], v[66:67], 0, v[74:75]
	global_load_dwordx2 v[36:37], v[4:5], off
	v_lshl_add_u64 v[4:5], v[4:5], 0, v[76:77]
	v_lshl_add_u64 v[70:71], v[68:69], 0, v[74:75]
	global_load_dwordx2 v[38:39], v[4:5], off
	v_lshl_add_u64 v[4:5], v[4:5], 0, v[76:77]
	v_lshl_add_u64 v[72:73], v[70:71], 0, v[74:75]
	global_load_dwordx2 v[40:41], v[4:5], off
	global_store_dword v[42:43], v7, off
	s_waitcnt vmcnt(16)
	v_fmac_f32_e32 v11, v7, v10
	global_store_dword v[44:45], v11, off
	s_waitcnt vmcnt(16)
	v_fmac_f32_e32 v13, v11, v12
	global_store_dword v[46:47], v13, off
	s_waitcnt vmcnt(16)
	v_fmac_f32_e32 v15, v13, v14
	global_store_dword v[48:49], v15, off
	s_waitcnt vmcnt(16)
	v_fmac_f32_e32 v17, v15, v16
	global_store_dword v[50:51], v17, off
	s_waitcnt vmcnt(16)
	v_fmac_f32_e32 v19, v17, v18
	global_store_dword v[52:53], v19, off
	s_waitcnt vmcnt(16)
	v_fmac_f32_e32 v21, v19, v20
	global_store_dword v[54:55], v21, off
	s_waitcnt vmcnt(16)
	v_fmac_f32_e32 v23, v21, v22
	global_store_dword v[56:57], v23, off
	s_waitcnt vmcnt(16)
	v_fmac_f32_e32 v25, v23, v24
	global_store_dword v[58:59], v25, off
	s_waitcnt vmcnt(16)
	v_fmac_f32_e32 v27, v25, v26
	global_store_dword v[60:61], v27, off
	s_waitcnt vmcnt(16)
	v_fmac_f32_e32 v29, v27, v28
	global_store_dword v[62:63], v29, off
	s_waitcnt vmcnt(16)
	v_fmac_f32_e32 v31, v29, v30
	global_store_dword v[64:65], v31, off
	s_waitcnt vmcnt(16)
	v_fmac_f32_e32 v33, v31, v32
	global_store_dword v[66:67], v33, off
	s_waitcnt vmcnt(16)
	v_fmac_f32_e32 v35, v33, v34
	global_store_dword v[68:69], v35, off
	s_waitcnt vmcnt(16)
	v_fmac_f32_e32 v37, v35, v36
	global_store_dword v[70:71], v37, off
	s_waitcnt vmcnt(16)
	v_fmac_f32_e32 v39, v37, v38
	global_store_dword v[72:73], v39, off
	s_waitcnt vmcnt(16)
	v_fmac_f32_e32 v41, v39, v40
	v_mov_b32_e32 v7, v41
	s_add_i32 s4, s4, 16
	s_add_i32 s5, s5, -16
	s_cmpk_eq_i32 s4, 0x100
	s_cbranch_scc0 .LBB0_503
	s_waitcnt vmcnt(0)
	v_readlane_b32 s2, v251, 43
	s_nop 1
	v_add_u32_e32 v1, s2, v1
	v_cmp_lt_i32_e32 vcc, s14, v1
	s_or_b64 s[24:25], vcc, s[24:25]
	s_andn2_b64 exec, exec, s[24:25]
	s_cbranch_execnz .LBB0_502
